# cache policy: non-temporal hint on the write-once h2 stores of the GEMM-up epilogue
# baseline (speedup 1.0000x reference)
; #define UFOR(v, n) _Pragma("unroll") for (int v = 0; v < (n); ++v)
; __device__ __forceinline__ unsigned pk2(float a, float b) { return (unsigned)f2bf(a) | ((unsigned)f2bf(b) << 16); }
; __device__ __forceinline__ float lo2f(unsigned u) { return __uint_as_float(u << 16); }
; __device__ __forceinline__ float hi2f(unsigned u) { return __uint_as_float(u & 0xffff0000u); }
; __device__ __forceinline__ float siluf_(float x) { return x / (1.f + __expf(-x)); }
; template <int EPI, int K, int KL> ...
;     ...
;       for (int q = 0; q < 16; ++q) {
;         const int lr = lr0 + q;
;         const int lrn = lr < 255 ? lr + 1 : 255;
;         const uint2 a = *(const uint2*)(U + lrn * 256 + c4), b = *(const uint2*)(U + lrn * 256 + 128 + c4);
;         ng[0] = lo2f(a.x); ng[1] = hi2f(a.x); ng[2] = lo2f(a.y); ng[3] = hi2f(a.y);
;         nv[0] = lo2f(b.x); nv[1] = hi2f(b.x); nv[2] = lo2f(b.y); nv[3] = hi2f(b.y);
;         const long gr = brow + lr;
;         const bool valid = (gr >= seq0) && (gr < seq1) && (lr >= 1 || gr == seq0) && (lr <= 254 || gr == seq1 - 1);
;         if (valid) {
;           const float mp = (gr - 1 >= seq0) ? 1.f : 0.f, mn = (gr + 1 < seq1) ? 1.f : 0.f;
;           float o[4];
;           UFOR(x, 4) {
;             const float g = wg[x][0] * pg[x] * mp + wg[x][1] * cgv[x] + wg[x][2] * ng[x] * mn;
;             const float v = wv[x][0] * pvv[x] * mp + wv[x][1] * cv[x] + wv[x][2] * nv[x] * mn;
;             o[x] = siluf_(g) * v;
;           }
;           uint2 pk; pk.x = pk2(o[0], o[1]); pk.y = pk2(o[2], o[3]);
;           *(uint2*)(e.h2 + (size_t)gr * DFF + gc) = pk;
;         }
.LBB0_1112:
	v_lshl_add_u64 v[52:53], v[132:133], 0, s[58:59]
	v_min_i32_e32 v36, 0xfe, v52
	v_add_u32_e32 v98, 1, v36
	v_and_b32_e32 v99, 15, v98
	v_xor_b32_e32 v99, v99, v96
	v_lshl_add_u32 v99, v99, 4, v97
	v_lshl_add_u32 v36, v98, 9, v99
	v_lshl_add_u64 v[54:55], v[28:29], 0, s[58:59]
	ds_read2_b64 v[40:43], v36 offset1:32
	v_cmp_le_i64_e32 vcc, s[50:51], v[54:55]
	v_cmp_gt_i64_e64 s[42:43], s[52:53], v[54:55]
	s_and_b64 s[62:63], vcc, s[42:43]
	v_cmp_lt_i32_e32 vcc, 0, v52
	v_cmp_eq_u64_e64 s[42:43], s[58:59], v[10:11]
	s_or_b64 s[42:43], vcc, s[42:43]
	s_and_b64 s[62:63], s[62:63], s[42:43]
	v_cmp_gt_i32_e32 vcc, s27, v52
	v_cmp_eq_u64_e64 s[42:43], s[58:59], v[32:33]
	s_or_b64 s[42:43], vcc, s[42:43]
	s_waitcnt lgkmcnt(0)
	v_lshlrev_b32_e32 v36, 16, v40
	v_lshlrev_b32_e32 v37, 16, v41
	v_and_b32_e32 v39, 0xffff0000, v41
	v_and_b32_e32 v38, 0xffff0000, v40
	v_lshlrev_b32_e32 v40, 16, v42
	v_lshlrev_b32_e32 v41, 16, v43
	v_and_b32_e32 v43, 0xffff0000, v43
	v_and_b32_e32 v42, 0xffff0000, v42
	s_and_b64 s[62:63], s[62:63], s[42:43]
	s_and_saveexec_b64 s[42:43], s[62:63]
	s_cbranch_execz .LBB0_1114
	v_cmp_lt_i64_e32 vcc, s[50:51], v[54:55]
	v_pk_mul_f32 v[58:59], v[12:13], v[58:59]
	v_pk_mul_f32 v[56:57], v[22:23], v[56:57]
	v_cndmask_b32_e64 v66, 0, 1.0, vcc
	v_cmp_gt_i64_e32 vcc, s[56:57], v[54:55]
	v_pk_mul_f32 v[58:59], v[58:59], v[66:67] op_sel_hi:[1,0]
	v_pk_mul_f32 v[70:71], v[14:15], v[36:37]
	v_cndmask_b32_e64 v68, 0, 1.0, vcc
	v_pk_fma_f32 v[58:59], v[0:1], v[46:47], v[58:59]
	v_pk_mul_f32 v[56:57], v[56:57], v[66:67] op_sel_hi:[1,0]
	v_pk_mul_f32 v[74:75], v[20:21], v[38:39]
	v_pk_fma_f32 v[58:59], v[70:71], v[68:69], v[58:59] op_sel_hi:[1,0,1]
	v_pk_fma_f32 v[56:57], v[8:9], v[44:45], v[56:57]
	v_mul_f32_e32 v53, 0xbfb8aa3b, v58
	v_pk_fma_f32 v[56:57], v[74:75], v[68:69], v[56:57] op_sel_hi:[1,0,1]
	v_exp_f32_e32 v70, v53
	v_mul_f32_e32 v53, 0xbfb8aa3b, v56
	v_exp_f32_e32 v74, v53
	v_mul_f32_e32 v53, 0xbfb8aa3b, v59
	v_exp_f32_e32 v71, v53
	v_pk_mul_f32 v[62:63], v[4:5], v[62:63]
	v_pk_mul_f32 v[72:73], v[6:7], v[40:41]
	v_pk_mul_f32 v[62:63], v[62:63], v[66:67] op_sel_hi:[1,0]
	v_pk_add_f32 v[70:71], v[70:71], 1.0 op_sel_hi:[1,0]
	v_pk_fma_f32 v[62:63], v[24:25], v[50:51], v[62:63]
	v_pk_fma_f32 v[62:63], v[68:69], v[72:73], v[62:63] op_sel_hi:[0,1,1]
	v_pk_mul_f32 v[60:61], v[18:19], v[60:61]
	v_pk_mul_f32 v[76:77], v[2:3], v[42:43]
	s_nop 0
	v_div_scale_f32 v80, vcc, v70, v70, v58
	v_div_scale_f32 v81, vcc, v71, v71, v59
	v_rcp_f32_e32 v82, v80
	v_rcp_f32_e32 v83, v81
	v_div_scale_f32 v86, s[62:63], v58, v70, v58
	v_div_scale_f32 v87, vcc, v59, v71, v59
	v_pk_fma_f32 v[84:85], v[80:81], v[82:83], 1.0 op_sel_hi:[1,1,0] neg_lo:[1,0,0] neg_hi:[1,0,0]
	v_pk_fma_f32 v[82:83], v[84:85], v[82:83], v[82:83]
	v_pk_mul_f32 v[88:89], v[86:87], v[82:83]
	v_pk_fma_f32 v[84:85], v[80:81], v[88:89], v[86:87] neg_lo:[1,0,0] neg_hi:[1,0,0]
	v_pk_fma_f32 v[88:89], v[84:85], v[82:83], v[88:89]
	v_pk_fma_f32 v[84:85], v[80:81], v[88:89], v[86:87] neg_lo:[1,0,0] neg_hi:[1,0,0]
	v_div_fmas_f32 v85, v85, v83, v89
	s_mov_b64 vcc, s[62:63]
	s_nop 0
	v_div_fmas_f32 v84, v84, v82, v88
	v_div_fixup_f32 v59, v85, v71, v59
	v_div_fixup_f32 v58, v84, v70, v58
	v_mul_f32_e32 v53, 0xbfb8aa3b, v57
	v_exp_f32_e32 v75, v53
	v_pk_mul_f32 v[58:59], v[62:63], v[58:59]
	v_pk_mul_f32 v[60:61], v[60:61], v[66:67] op_sel_hi:[1,0]
	v_pk_add_f32 v[62:63], v[74:75], 1.0 op_sel_hi:[1,0]
	s_nop 0
	v_pk_fma_f32 v[60:61], v[16:17], v[48:49], v[60:61]
	v_pk_fma_f32 v[60:61], v[68:69], v[76:77], v[60:61] op_sel_hi:[0,1,1]
	s_nop 0
	v_div_scale_f32 v80, vcc, v62, v62, v56
	v_div_scale_f32 v81, vcc, v63, v63, v57
	v_rcp_f32_e32 v82, v80
	v_rcp_f32_e32 v83, v81
	v_div_scale_f32 v86, s[62:63], v56, v62, v56
	v_div_scale_f32 v87, vcc, v57, v63, v57
	v_pk_fma_f32 v[84:85], v[80:81], v[82:83], 1.0 op_sel_hi:[1,1,0] neg_lo:[1,0,0] neg_hi:[1,0,0]
	v_pk_fma_f32 v[82:83], v[84:85], v[82:83], v[82:83]
	v_pk_mul_f32 v[88:89], v[86:87], v[82:83]
	v_pk_fma_f32 v[84:85], v[80:81], v[88:89], v[86:87] neg_lo:[1,0,0] neg_hi:[1,0,0]
	v_pk_fma_f32 v[88:89], v[84:85], v[82:83], v[88:89]
	v_pk_fma_f32 v[84:85], v[80:81], v[88:89], v[86:87] neg_lo:[1,0,0] neg_hi:[1,0,0]
	v_div_fmas_f32 v85, v85, v83, v89
	s_mov_b64 vcc, s[62:63]
	s_nop 0
	v_div_fmas_f32 v84, v84, v82, v88
	v_div_fixup_f32 v57, v85, v63, v57
	v_div_fixup_f32 v56, v84, v62, v56
	v_pk_mul_f32 v[56:57], v[60:61], v[56:57]
	v_cvt_pk_bf16_f32 v56, v58, v56
	v_cvt_pk_bf16_f32 v57, v59, v57
	v_add_co_u32_e32 v58, vcc, 0xffffe000, v30
	s_nop 1
	v_addc_co_u32_e32 v59, vcc, -1, v31, vcc
	global_store_dwordx2 v[58:59], v[56:57], off offset:-3072 nt
; #define UFOR(v, n) _Pragma("unroll") for (int v = 0; v < (n); ++v)
; __device__ __forceinline__ unsigned pk2(float a, float b) { return (unsigned)f2bf(a) | ((unsigned)f2bf(b) << 16); }
; __device__ __forceinline__ float lo2f(unsigned u) { return __uint_as_float(u << 16); }
; __device__ __forceinline__ float hi2f(unsigned u) { return __uint_as_float(u & 0xffff0000u); }
; __device__ __forceinline__ float siluf_(float x) { return x / (1.f + __expf(-x)); }
; template <int EPI, int K, int KL> ...
;     ...
;       for (int q = 0; q < 16; ++q) {
;         const int lr = lr0 + q;
;         const int lrn = lr < 255 ? lr + 1 : 255;
;         const uint2 a = *(const uint2*)(U + lrn * 256 + c4), b = *(const uint2*)(U + lrn * 256 + 128 + c4);
;         ng[0] = lo2f(a.x); ng[1] = hi2f(a.x); ng[2] = lo2f(a.y); ng[3] = hi2f(a.y);
;         nv[0] = lo2f(b.x); nv[1] = hi2f(b.x); nv[2] = lo2f(b.y); nv[3] = hi2f(b.y);
;         const long gr = brow + lr;
;         const bool valid = (gr >= seq0) && (gr < seq1) && (lr >= 1 || gr == seq0) && (lr <= 254 || gr == seq1 - 1);
;         if (valid) {
;           const float mp = (gr - 1 >= seq0) ? 1.f : 0.f, mn = (gr + 1 < seq1) ? 1.f : 0.f;
;           float o[4];
;           UFOR(x, 4) {
;             const float g = wg[x][0] * pg[x] * mp + wg[x][1] * cgv[x] + wg[x][2] * ng[x] * mn;
;             const float v = wv[x][0] * pvv[x] * mp + wv[x][1] * cv[x] + wv[x][2] * nv[x] * mn;
;             o[x] = siluf_(g) * v;
;           }
;           uint2 pk; pk.x = pk2(o[0], o[1]); pk.y = pk2(o[2], o[3]);
;           *(uint2*)(e.h2 + (size_t)gr * DFF + gc) = pk;
;         }
;         UFOR(x, 4) { pg[x] = cgv[x]; cgv[x] = ng[x]; pvv[x] = cv[x]; cv[x] = nv[x]; }
;       }
.LBB0_1114:
	s_or_b64 exec, exec, s[42:43]
	v_add_u32_e32 v62, 1, v52
	v_min_i32_e32 v52, 0xfe, v62
	v_add_u32_e32 v98, 1, v52
	v_and_b32_e32 v99, 15, v98
	v_xor_b32_e32 v99, v99, v96
	v_lshl_add_u32 v99, v99, 4, v97
	v_lshl_add_u32 v52, v98, 9, v99
	v_lshl_add_u64 v[54:55], v[54:55], 0, 1
	ds_read2_b64 v[58:61], v52 offset1:32
	v_cmp_le_i64_e32 vcc, s[50:51], v[54:55]
	v_cmp_gt_i64_e64 s[42:43], s[52:53], v[54:55]
	s_and_b64 s[42:43], vcc, s[42:43]
	v_cmp_eq_u64_e32 vcc, s[58:59], v[26:27]
	s_or_b64 s[62:63], s[40:41], vcc
	s_and_b64 s[62:63], s[42:43], s[62:63]
	v_cmp_gt_i32_e32 vcc, s27, v62
	v_cmp_eq_u64_e64 s[42:43], s[58:59], v[34:35]
	s_or_b64 s[42:43], vcc, s[42:43]
	s_waitcnt lgkmcnt(0)
	v_lshlrev_b32_e32 v52, 16, v58
	v_lshlrev_b32_e32 v53, 16, v59
	v_and_b32_e32 v57, 0xffff0000, v59
	v_and_b32_e32 v56, 0xffff0000, v58
	v_lshlrev_b32_e32 v58, 16, v60
	v_lshlrev_b32_e32 v59, 16, v61
	v_and_b32_e32 v61, 0xffff0000, v61
	v_and_b32_e32 v60, 0xffff0000, v60
	s_and_b64 s[62:63], s[62:63], s[42:43]
	s_and_saveexec_b64 s[42:43], s[62:63]
	s_cbranch_execz .LBB0_1111
	v_cmp_lt_i64_e32 vcc, s[50:51], v[54:55]
	v_pk_mul_f32 v[46:47], v[12:13], v[46:47]
	v_pk_mul_f32 v[66:67], v[14:15], v[52:53]
	v_cndmask_b32_e64 v62, 0, 1.0, vcc
	v_cmp_gt_i64_e32 vcc, s[56:57], v[54:55]
	v_pk_mul_f32 v[46:47], v[46:47], v[62:63] op_sel_hi:[1,0]
	v_pk_mul_f32 v[44:45], v[22:23], v[44:45]
	v_cndmask_b32_e64 v54, 0, 1.0, vcc
	v_pk_fma_f32 v[46:47], v[0:1], v[36:37], v[46:47]
	v_pk_mul_f32 v[44:45], v[44:45], v[62:63] op_sel_hi:[1,0]
	v_pk_fma_f32 v[46:47], v[66:67], v[54:55], v[46:47] op_sel_hi:[1,0,1]
	v_pk_mul_f32 v[50:51], v[4:5], v[50:51]
	v_pk_mul_f32 v[70:71], v[20:21], v[56:57]
	v_mul_f32_e32 v55, 0xbfb8aa3b, v46
	v_pk_fma_f32 v[44:45], v[8:9], v[38:39], v[44:45]
	v_pk_mul_f32 v[50:51], v[50:51], v[62:63] op_sel_hi:[1,0]
	v_pk_fma_f32 v[44:45], v[70:71], v[54:55], v[44:45] op_sel_hi:[1,0,1]
	v_pk_mul_f32 v[68:69], v[6:7], v[58:59]
	v_exp_f32_e32 v66, v55
	v_mul_f32_e32 v55, 0xbfb8aa3b, v44
	v_pk_fma_f32 v[50:51], v[24:25], v[40:41], v[50:51]
	v_exp_f32_e32 v70, v55
	v_pk_fma_f32 v[50:51], v[54:55], v[68:69], v[50:51] op_sel_hi:[0,1,1]
	v_mul_f32_e32 v55, 0xbfb8aa3b, v47
	v_exp_f32_e32 v67, v55
	v_pk_mul_f32 v[48:49], v[18:19], v[48:49]
	v_pk_mul_f32 v[72:73], v[2:3], v[60:61]
	v_pk_add_f32 v[66:67], v[66:67], 1.0 op_sel_hi:[1,0]
	s_nop 0
	s_nop 0
	s_nop 0
	v_div_scale_f32 v80, vcc, v66, v66, v46
	v_div_scale_f32 v81, vcc, v67, v67, v47
	v_rcp_f32_e32 v82, v80
	v_rcp_f32_e32 v83, v81
	v_div_scale_f32 v86, s[62:63], v46, v66, v46
	v_div_scale_f32 v87, vcc, v47, v67, v47
	v_pk_fma_f32 v[84:85], v[80:81], v[82:83], 1.0 op_sel_hi:[1,1,0] neg_lo:[1,0,0] neg_hi:[1,0,0]
	v_pk_fma_f32 v[82:83], v[84:85], v[82:83], v[82:83]
	v_pk_mul_f32 v[88:89], v[86:87], v[82:83]
	v_pk_fma_f32 v[84:85], v[80:81], v[88:89], v[86:87] neg_lo:[1,0,0] neg_hi:[1,0,0]
	v_pk_fma_f32 v[88:89], v[84:85], v[82:83], v[88:89]
	v_pk_fma_f32 v[84:85], v[80:81], v[88:89], v[86:87] neg_lo:[1,0,0] neg_hi:[1,0,0]
	v_div_fmas_f32 v85, v85, v83, v89
	s_mov_b64 vcc, s[62:63]
	s_nop 0
	v_div_fmas_f32 v84, v84, v82, v88
	v_div_fixup_f32 v47, v85, v67, v47
	v_div_fixup_f32 v46, v84, v66, v46
	v_pk_mul_f32 v[46:47], v[50:51], v[46:47]
	v_mul_f32_e32 v50, 0xbfb8aa3b, v45
	v_exp_f32_e32 v71, v50
	v_pk_mul_f32 v[48:49], v[48:49], v[62:63] op_sel_hi:[1,0]
	v_pk_add_f32 v[50:51], v[70:71], 1.0 op_sel_hi:[1,0]
	v_pk_fma_f32 v[48:49], v[16:17], v[42:43], v[48:49]
	s_nop 0
	v_pk_fma_f32 v[48:49], v[54:55], v[72:73], v[48:49] op_sel_hi:[0,1,1]
	s_nop 0
	s_nop 0
	v_div_scale_f32 v80, vcc, v50, v50, v44
	v_div_scale_f32 v81, vcc, v51, v51, v45
	v_rcp_f32_e32 v82, v80
	v_rcp_f32_e32 v83, v81
	v_div_scale_f32 v86, s[62:63], v44, v50, v44
	v_div_scale_f32 v87, vcc, v45, v51, v45
	v_pk_fma_f32 v[84:85], v[80:81], v[82:83], 1.0 op_sel_hi:[1,1,0] neg_lo:[1,0,0] neg_hi:[1,0,0]
	v_pk_fma_f32 v[82:83], v[84:85], v[82:83], v[82:83]
	v_pk_mul_f32 v[88:89], v[86:87], v[82:83]
	v_pk_fma_f32 v[84:85], v[80:81], v[88:89], v[86:87] neg_lo:[1,0,0] neg_hi:[1,0,0]
	v_pk_fma_f32 v[88:89], v[84:85], v[82:83], v[88:89]
	v_pk_fma_f32 v[84:85], v[80:81], v[88:89], v[86:87] neg_lo:[1,0,0] neg_hi:[1,0,0]
	v_div_fmas_f32 v85, v85, v83, v89
	s_mov_b64 vcc, s[62:63]
	s_nop 0
	v_div_fmas_f32 v84, v84, v82, v88
	v_div_fixup_f32 v45, v85, v51, v45
	v_div_fixup_f32 v44, v84, v50, v44
	v_pk_mul_f32 v[44:45], v[48:49], v[44:45]
	v_cvt_pk_bf16_f32 v45, v47, v45
	v_cvt_pk_bf16_f32 v44, v46, v44
	global_store_dwordx2 v[30:31], v[44:45], off nt
	s_branch .LBB0_1111
